# P3 SSD carry scan: depth-16 software-prefetched fast path for prompt lanes
# speedup vs baseline: 1.0274x; 1.0274x over previous
; __device__ __forceinline__ float bf2f(unsigned v) { return __uint_as_float(v << 16); }
; __device__ __forceinline__ unsigned pk2(float lo, float hi) { f32x2 v; v.x = lo; v.y = hi; return __builtin_bit_cast(unsigned, __builtin_convertvector(v, hwbf2)); }
; __global__ void __launch_bounds__(512, 2) fwd_kernel(Args a) {
;     ...
;         bf16_t* sst = (bf16_t*)(ws + WS_SST); const float* cdec = (const float*)(ws + WS_CDEC);
;         for (int i = bx * 512 + tid; i < 16 * 8 * 2048; i += G * 512) {
;             const int sq = i >> 14, h = (i >> 11) & 7, e4 = (i & 2047) * 4;
;             const bool smp = sq >= 8; const int b = sq & 7;
;             const int nch = smp ? 1 : NCHUNK, slot0 = smp ? NBATCH * NCHUNK + b : b * NCHUNK;
;             f32x4 hc = (f32x4){0.f, 0.f, 0.f, 0.f};
;             if (smp) hc = *(const f32x4*)(a.in[I_SSSD] + ((size_t)(b * 8 + h) * 8192 + e4));
;             for (int c = 0; c < nch; ++c) {
;                 u32x2* p = (u32x2*)(sst + ((size_t)(slot0 + c) * 8 + h) * 8192 + e4);
;                 const u32x2 w = *p; const float d = cdec[(size_t)(slot0 + c) * 8 + h];
;                 u32x2 o; o.x = pk2(hc[0], hc[1]); o.y = pk2(hc[2], hc[3]); *p = o;
;                 hc[0] = hc[0] * d + bf2f(w.x & 0xffff); hc[1] = hc[1] * d + bf2f(w.x >> 16); hc[2] = hc[2] * d + bf2f(w.y & 0xffff); hc[3] = hc[3] * d + bf2f(w.y >> 16);
.LBB0_539:
	s_or_b64 exec, exec, s[14:15]
	v_lshrrev_b32_e32 v8, 11, v14
	v_and_b32_e32 v8, 7, v8
	v_lshlrev_b32_e32 v9, 2, v8
	v_lshlrev_b32_e32 v10, 14, v8
	v_lshlrev_b32_e32 v8, 1, v5
	v_and_b32_e32 v11, 0x3ff8, v8
	v_or_b32_e32 v8, 0x400, v6
	v_lshlrev_b32_e32 v6, 7, v6
	v_cndmask_b32_e32 v16, v8, v6, vcc
	v_lshl_or_b32 v6, v16, 5, v9
	v_lshl_add_u64 v[8:9], s[4:5], 0, v[6:7]
	v_lshlrev_b32_e32 v6, 17, v16
	v_or3_b32 v6, v6, v10, v11
	v_lshl_add_u64 v[10:11], s[8:9], 0, v[6:7]
	s_mov_b32 s19, 0
	s_mov_b64 s[0:1], 0
	s_xor_b64 s[14:15], vcc, -1
	s_and_b64 s[36:37], vcc, exec
	s_cmp_eq_u64 s[36:37], exec
	s_cbranch_scc0 .LBB0_540
	s_mov_b32 s36, s8
	s_mov_b32 s37, s9
	v_add_u32_e32 v156, 0x200000, v6
	s_mov_b32 s46, 0x200
	s_mov_b32 s47, 0
	global_load_dwordx2 v[100:101], v6, s[36:37]
	global_load_dword v132, v[8:9], off offset:0
	global_load_dword v132, v[8:9], off offset:0
	s_add_u32 s36, s36, 0x20000
	s_addc_u32 s37, s37, 0
	global_load_dwordx2 v[102:103], v6, s[36:37]
	global_load_dword v133, v[8:9], off offset:32
	global_load_dword v133, v[8:9], off offset:32
	s_add_u32 s36, s36, 0x20000
	s_addc_u32 s37, s37, 0
	global_load_dwordx2 v[104:105], v6, s[36:37]
	global_load_dword v134, v[8:9], off offset:64
	global_load_dword v134, v[8:9], off offset:64
	s_add_u32 s36, s36, 0x20000
	s_addc_u32 s37, s37, 0
	global_load_dwordx2 v[106:107], v6, s[36:37]
	global_load_dword v135, v[8:9], off offset:96
	global_load_dword v135, v[8:9], off offset:96
	s_add_u32 s36, s36, 0x20000
	s_addc_u32 s37, s37, 0
	global_load_dwordx2 v[108:109], v6, s[36:37]
	global_load_dword v136, v[8:9], off offset:128
	global_load_dword v136, v[8:9], off offset:128
	s_add_u32 s36, s36, 0x20000
	s_addc_u32 s37, s37, 0
	global_load_dwordx2 v[110:111], v6, s[36:37]
	global_load_dword v137, v[8:9], off offset:160
	global_load_dword v137, v[8:9], off offset:160
	s_add_u32 s36, s36, 0x20000
	s_addc_u32 s37, s37, 0
	global_load_dwordx2 v[112:113], v6, s[36:37]
	global_load_dword v138, v[8:9], off offset:192
	global_load_dword v138, v[8:9], off offset:192
	s_add_u32 s36, s36, 0x20000
	s_addc_u32 s37, s37, 0
	global_load_dwordx2 v[114:115], v6, s[36:37]
	global_load_dword v139, v[8:9], off offset:224
	global_load_dword v139, v[8:9], off offset:224
	s_add_u32 s36, s36, 0x20000
	s_addc_u32 s37, s37, 0
	global_load_dwordx2 v[116:117], v6, s[36:37]
	global_load_dword v140, v[8:9], off offset:256
	global_load_dword v140, v[8:9], off offset:256
	s_add_u32 s36, s36, 0x20000
	s_addc_u32 s37, s37, 0
	global_load_dwordx2 v[118:119], v6, s[36:37]
	global_load_dword v141, v[8:9], off offset:288
	global_load_dword v141, v[8:9], off offset:288
	s_add_u32 s36, s36, 0x20000
	s_addc_u32 s37, s37, 0
	global_load_dwordx2 v[120:121], v6, s[36:37]
	global_load_dword v142, v[8:9], off offset:320
	global_load_dword v142, v[8:9], off offset:320
	s_add_u32 s36, s36, 0x20000
	s_addc_u32 s37, s37, 0
	global_load_dwordx2 v[122:123], v6, s[36:37]
	global_load_dword v143, v[8:9], off offset:352
	global_load_dword v143, v[8:9], off offset:352
	s_add_u32 s36, s36, 0x20000
	s_addc_u32 s37, s37, 0
	global_load_dwordx2 v[124:125], v6, s[36:37]
	global_load_dword v144, v[8:9], off offset:384
	global_load_dword v144, v[8:9], off offset:384
	s_add_u32 s36, s36, 0x20000
	s_addc_u32 s37, s37, 0
	global_load_dwordx2 v[126:127], v6, s[36:37]
	global_load_dword v145, v[8:9], off offset:416
	global_load_dword v145, v[8:9], off offset:416
	s_add_u32 s36, s36, 0x20000
	s_addc_u32 s37, s37, 0
	global_load_dwordx2 v[128:129], v6, s[36:37]
	global_load_dword v146, v[8:9], off offset:448
	global_load_dword v146, v[8:9], off offset:448
	s_add_u32 s36, s36, 0x20000
	s_addc_u32 s37, s37, 0
	global_load_dwordx2 v[130:131], v6, s[36:37]
	global_load_dword v147, v[8:9], off offset:480
	global_load_dword v147, v[8:9], off offset:480
	s_add_u32 s36, s36, 0x20000
	s_addc_u32 s37, s37, 0
	s_mov_b32 s36, s8
	s_mov_b32 s37, s9
	s_mov_b32 s38, 7
.Lp3_fast_loop:
	s_waitcnt vmcnt(45)
	v_cvt_pk_bf16_f32 v148, v0, v1
	v_cvt_pk_bf16_f32 v149, v2, v3
	global_store_dwordx2 v6, v[148:149], s[36:37]
	v_lshlrev_b32_e32 v150, 16, v100
	v_and_b32_e32 v151, 0xffff0000, v100
	v_lshlrev_b32_e32 v152, 16, v101
	v_and_b32_e32 v153, 0xffff0000, v101
	v_fma_f32 v0, v0, v132, v150
	v_fma_f32 v1, v1, v132, v151
	v_fma_f32 v2, v2, v132, v152
	v_fma_f32 v3, v3, v132, v153
	global_load_dwordx2 v[100:101], v156, s[36:37]
	global_load_dword v132, v[8:9], off offset:512
	s_add_u32 s36, s36, 0x20000
	s_addc_u32 s37, s37, 0
	s_waitcnt vmcnt(45)
	v_cvt_pk_bf16_f32 v154, v0, v1
	v_cvt_pk_bf16_f32 v155, v2, v3
	global_store_dwordx2 v6, v[154:155], s[36:37]
	v_lshlrev_b32_e32 v150, 16, v102
	v_and_b32_e32 v151, 0xffff0000, v102
	v_lshlrev_b32_e32 v152, 16, v103
	v_and_b32_e32 v153, 0xffff0000, v103
	v_fma_f32 v0, v0, v133, v150
	v_fma_f32 v1, v1, v133, v151
	v_fma_f32 v2, v2, v133, v152
	v_fma_f32 v3, v3, v133, v153
	global_load_dwordx2 v[102:103], v156, s[36:37]
	global_load_dword v133, v[8:9], off offset:544
	s_add_u32 s36, s36, 0x20000
	s_addc_u32 s37, s37, 0
	s_waitcnt vmcnt(45)
	v_cvt_pk_bf16_f32 v148, v0, v1
	v_cvt_pk_bf16_f32 v149, v2, v3
	global_store_dwordx2 v6, v[148:149], s[36:37]
	v_lshlrev_b32_e32 v150, 16, v104
	v_and_b32_e32 v151, 0xffff0000, v104
	v_lshlrev_b32_e32 v152, 16, v105
	v_and_b32_e32 v153, 0xffff0000, v105
	v_fma_f32 v0, v0, v134, v150
	v_fma_f32 v1, v1, v134, v151
	v_fma_f32 v2, v2, v134, v152
	v_fma_f32 v3, v3, v134, v153
	global_load_dwordx2 v[104:105], v156, s[36:37]
	global_load_dword v134, v[8:9], off offset:576
	s_add_u32 s36, s36, 0x20000
	s_addc_u32 s37, s37, 0
	s_waitcnt vmcnt(45)
; __device__ __forceinline__ float bf2f(unsigned v) { return __uint_as_float(v << 16); }
; __device__ __forceinline__ unsigned pk2(float lo, float hi) { f32x2 v; v.x = lo; v.y = hi; return __builtin_bit_cast(unsigned, __builtin_convertvector(v, hwbf2)); }
; __global__ void __launch_bounds__(512, 2) fwd_kernel(Args a) {
;     ...
;             for (int c = 0; c < nch; ++c) {
;                 u32x2* p = (u32x2*)(sst + ((size_t)(slot0 + c) * 8 + h) * 8192 + e4);
;                 const u32x2 w = *p; const float d = cdec[(size_t)(slot0 + c) * 8 + h];
;                 u32x2 o; o.x = pk2(hc[0], hc[1]); o.y = pk2(hc[2], hc[3]); *p = o;
;                 hc[0] = hc[0] * d + bf2f(w.x & 0xffff); hc[1] = hc[1] * d + bf2f(w.x >> 16); hc[2] = hc[2] * d + bf2f(w.y & 0xffff); hc[3] = hc[3] * d + bf2f(w.y >> 16);
	v_cvt_pk_bf16_f32 v154, v0, v1
	v_cvt_pk_bf16_f32 v155, v2, v3
	global_store_dwordx2 v6, v[154:155], s[36:37]
	v_lshlrev_b32_e32 v150, 16, v106
	v_and_b32_e32 v151, 0xffff0000, v106
	v_lshlrev_b32_e32 v152, 16, v107
	v_and_b32_e32 v153, 0xffff0000, v107
	v_fma_f32 v0, v0, v135, v150
	v_fma_f32 v1, v1, v135, v151
	v_fma_f32 v2, v2, v135, v152
	v_fma_f32 v3, v3, v135, v153
	global_load_dwordx2 v[106:107], v156, s[36:37]
	global_load_dword v135, v[8:9], off offset:608
	s_add_u32 s36, s36, 0x20000
	s_addc_u32 s37, s37, 0
	s_waitcnt vmcnt(45)
	v_cvt_pk_bf16_f32 v148, v0, v1
	v_cvt_pk_bf16_f32 v149, v2, v3
	global_store_dwordx2 v6, v[148:149], s[36:37]
	v_lshlrev_b32_e32 v150, 16, v108
	v_and_b32_e32 v151, 0xffff0000, v108
	v_lshlrev_b32_e32 v152, 16, v109
	v_and_b32_e32 v153, 0xffff0000, v109
	v_fma_f32 v0, v0, v136, v150
	v_fma_f32 v1, v1, v136, v151
	v_fma_f32 v2, v2, v136, v152
	v_fma_f32 v3, v3, v136, v153
	global_load_dwordx2 v[108:109], v156, s[36:37]
	global_load_dword v136, v[8:9], off offset:640
	s_add_u32 s36, s36, 0x20000
	s_addc_u32 s37, s37, 0
	s_waitcnt vmcnt(45)
	v_cvt_pk_bf16_f32 v154, v0, v1
	v_cvt_pk_bf16_f32 v155, v2, v3
	global_store_dwordx2 v6, v[154:155], s[36:37]
	v_lshlrev_b32_e32 v150, 16, v110
	v_and_b32_e32 v151, 0xffff0000, v110
	v_lshlrev_b32_e32 v152, 16, v111
	v_and_b32_e32 v153, 0xffff0000, v111
	v_fma_f32 v0, v0, v137, v150
	v_fma_f32 v1, v1, v137, v151
	v_fma_f32 v2, v2, v137, v152
	v_fma_f32 v3, v3, v137, v153
	global_load_dwordx2 v[110:111], v156, s[36:37]
	global_load_dword v137, v[8:9], off offset:672
	s_add_u32 s36, s36, 0x20000
	s_addc_u32 s37, s37, 0
	s_waitcnt vmcnt(45)
	v_cvt_pk_bf16_f32 v148, v0, v1
	v_cvt_pk_bf16_f32 v149, v2, v3
	global_store_dwordx2 v6, v[148:149], s[36:37]
	v_lshlrev_b32_e32 v150, 16, v112
	v_and_b32_e32 v151, 0xffff0000, v112
	v_lshlrev_b32_e32 v152, 16, v113
	v_and_b32_e32 v153, 0xffff0000, v113
	v_fma_f32 v0, v0, v138, v150
	v_fma_f32 v1, v1, v138, v151
	v_fma_f32 v2, v2, v138, v152
	v_fma_f32 v3, v3, v138, v153
	global_load_dwordx2 v[112:113], v156, s[36:37]
	global_load_dword v138, v[8:9], off offset:704
	s_add_u32 s36, s36, 0x20000
	s_addc_u32 s37, s37, 0
	s_waitcnt vmcnt(45)
	v_cvt_pk_bf16_f32 v154, v0, v1
	v_cvt_pk_bf16_f32 v155, v2, v3
	global_store_dwordx2 v6, v[154:155], s[36:37]
	v_lshlrev_b32_e32 v150, 16, v114
	v_and_b32_e32 v151, 0xffff0000, v114
	v_lshlrev_b32_e32 v152, 16, v115
	v_and_b32_e32 v153, 0xffff0000, v115
	v_fma_f32 v0, v0, v139, v150
	v_fma_f32 v1, v1, v139, v151
	v_fma_f32 v2, v2, v139, v152
	v_fma_f32 v3, v3, v139, v153
	global_load_dwordx2 v[114:115], v156, s[36:37]
	global_load_dword v139, v[8:9], off offset:736
	s_add_u32 s36, s36, 0x20000
	s_addc_u32 s37, s37, 0
	s_waitcnt vmcnt(45)
	v_cvt_pk_bf16_f32 v148, v0, v1
	v_cvt_pk_bf16_f32 v149, v2, v3
	global_store_dwordx2 v6, v[148:149], s[36:37]
	v_lshlrev_b32_e32 v150, 16, v116
	v_and_b32_e32 v151, 0xffff0000, v116
	v_lshlrev_b32_e32 v152, 16, v117
	v_and_b32_e32 v153, 0xffff0000, v117
	v_fma_f32 v0, v0, v140, v150
	v_fma_f32 v1, v1, v140, v151
	v_fma_f32 v2, v2, v140, v152
	v_fma_f32 v3, v3, v140, v153
	global_load_dwordx2 v[116:117], v156, s[36:37]
	global_load_dword v140, v[8:9], off offset:768
	s_add_u32 s36, s36, 0x20000
	s_addc_u32 s37, s37, 0
	s_waitcnt vmcnt(45)
	v_cvt_pk_bf16_f32 v154, v0, v1
	v_cvt_pk_bf16_f32 v155, v2, v3
	global_store_dwordx2 v6, v[154:155], s[36:37]
	v_lshlrev_b32_e32 v150, 16, v118
	v_and_b32_e32 v151, 0xffff0000, v118
	v_lshlrev_b32_e32 v152, 16, v119
	v_and_b32_e32 v153, 0xffff0000, v119
	v_fma_f32 v0, v0, v141, v150
	v_fma_f32 v1, v1, v141, v151
	v_fma_f32 v2, v2, v141, v152
	v_fma_f32 v3, v3, v141, v153
	global_load_dwordx2 v[118:119], v156, s[36:37]
	global_load_dword v141, v[8:9], off offset:800
	s_add_u32 s36, s36, 0x20000
	s_addc_u32 s37, s37, 0
	s_waitcnt vmcnt(45)
	v_cvt_pk_bf16_f32 v148, v0, v1
	v_cvt_pk_bf16_f32 v149, v2, v3
	global_store_dwordx2 v6, v[148:149], s[36:37]
	v_lshlrev_b32_e32 v150, 16, v120
	v_and_b32_e32 v151, 0xffff0000, v120
	v_lshlrev_b32_e32 v152, 16, v121
	v_and_b32_e32 v153, 0xffff0000, v121
	v_fma_f32 v0, v0, v142, v150
	v_fma_f32 v1, v1, v142, v151
	v_fma_f32 v2, v2, v142, v152
	v_fma_f32 v3, v3, v142, v153
	global_load_dwordx2 v[120:121], v156, s[36:37]
	global_load_dword v142, v[8:9], off offset:832
	s_add_u32 s36, s36, 0x20000
	s_addc_u32 s37, s37, 0
	s_waitcnt vmcnt(45)
	v_cvt_pk_bf16_f32 v154, v0, v1
	v_cvt_pk_bf16_f32 v155, v2, v3
	global_store_dwordx2 v6, v[154:155], s[36:37]
	v_lshlrev_b32_e32 v150, 16, v122
	v_and_b32_e32 v151, 0xffff0000, v122
	v_lshlrev_b32_e32 v152, 16, v123
	v_and_b32_e32 v153, 0xffff0000, v123
	v_fma_f32 v0, v0, v143, v150
	v_fma_f32 v1, v1, v143, v151
	v_fma_f32 v2, v2, v143, v152
	v_fma_f32 v3, v3, v143, v153
	global_load_dwordx2 v[122:123], v156, s[36:37]
	global_load_dword v143, v[8:9], off offset:864
	s_add_u32 s36, s36, 0x20000
	s_addc_u32 s37, s37, 0
	s_waitcnt vmcnt(45)
	v_cvt_pk_bf16_f32 v148, v0, v1
	v_cvt_pk_bf16_f32 v149, v2, v3
	global_store_dwordx2 v6, v[148:149], s[36:37]
	v_lshlrev_b32_e32 v150, 16, v124
	v_and_b32_e32 v151, 0xffff0000, v124
	v_lshlrev_b32_e32 v152, 16, v125
	v_and_b32_e32 v153, 0xffff0000, v125
	v_fma_f32 v0, v0, v144, v150
	v_fma_f32 v1, v1, v144, v151
	v_fma_f32 v2, v2, v144, v152
	v_fma_f32 v3, v3, v144, v153
	global_load_dwordx2 v[124:125], v156, s[36:37]
	global_load_dword v144, v[8:9], off offset:896
	s_add_u32 s36, s36, 0x20000
	s_addc_u32 s37, s37, 0
	s_waitcnt vmcnt(45)
; __device__ __forceinline__ float bf2f(unsigned v) { return __uint_as_float(v << 16); }
; __device__ __forceinline__ unsigned pk2(float lo, float hi) { f32x2 v; v.x = lo; v.y = hi; return __builtin_bit_cast(unsigned, __builtin_convertvector(v, hwbf2)); }
; __global__ void __launch_bounds__(512, 2) fwd_kernel(Args a) {
;     ...
;             for (int c = 0; c < nch; ++c) {
;                 u32x2* p = (u32x2*)(sst + ((size_t)(slot0 + c) * 8 + h) * 8192 + e4);
;                 const u32x2 w = *p; const float d = cdec[(size_t)(slot0 + c) * 8 + h];
;                 u32x2 o; o.x = pk2(hc[0], hc[1]); o.y = pk2(hc[2], hc[3]); *p = o;
;                 hc[0] = hc[0] * d + bf2f(w.x & 0xffff); hc[1] = hc[1] * d + bf2f(w.x >> 16); hc[2] = hc[2] * d + bf2f(w.y & 0xffff); hc[3] = hc[3] * d + bf2f(w.y >> 16);
	v_cvt_pk_bf16_f32 v154, v0, v1
	v_cvt_pk_bf16_f32 v155, v2, v3
	global_store_dwordx2 v6, v[154:155], s[36:37]
	v_lshlrev_b32_e32 v150, 16, v126
	v_and_b32_e32 v151, 0xffff0000, v126
	v_lshlrev_b32_e32 v152, 16, v127
	v_and_b32_e32 v153, 0xffff0000, v127
	v_fma_f32 v0, v0, v145, v150
	v_fma_f32 v1, v1, v145, v151
	v_fma_f32 v2, v2, v145, v152
	v_fma_f32 v3, v3, v145, v153
	global_load_dwordx2 v[126:127], v156, s[36:37]
	global_load_dword v145, v[8:9], off offset:928
	s_add_u32 s36, s36, 0x20000
	s_addc_u32 s37, s37, 0
	s_waitcnt vmcnt(45)
	v_cvt_pk_bf16_f32 v148, v0, v1
	v_cvt_pk_bf16_f32 v149, v2, v3
	global_store_dwordx2 v6, v[148:149], s[36:37]
	v_lshlrev_b32_e32 v150, 16, v128
	v_and_b32_e32 v151, 0xffff0000, v128
	v_lshlrev_b32_e32 v152, 16, v129
	v_and_b32_e32 v153, 0xffff0000, v129
	v_fma_f32 v0, v0, v146, v150
	v_fma_f32 v1, v1, v146, v151
	v_fma_f32 v2, v2, v146, v152
	v_fma_f32 v3, v3, v146, v153
	global_load_dwordx2 v[128:129], v156, s[36:37]
	global_load_dword v146, v[8:9], off offset:960
	s_add_u32 s36, s36, 0x20000
	s_addc_u32 s37, s37, 0
	s_waitcnt vmcnt(45)
	v_cvt_pk_bf16_f32 v154, v0, v1
	v_cvt_pk_bf16_f32 v155, v2, v3
	global_store_dwordx2 v6, v[154:155], s[36:37]
	v_lshlrev_b32_e32 v150, 16, v130
	v_and_b32_e32 v151, 0xffff0000, v130
	v_lshlrev_b32_e32 v152, 16, v131
	v_and_b32_e32 v153, 0xffff0000, v131
	v_fma_f32 v0, v0, v147, v150
	v_fma_f32 v1, v1, v147, v151
	v_fma_f32 v2, v2, v147, v152
	v_fma_f32 v3, v3, v147, v153
	global_load_dwordx2 v[130:131], v156, s[36:37]
	global_load_dword v147, v[8:9], off offset:992
	s_add_u32 s36, s36, 0x20000
	s_addc_u32 s37, s37, 0
	v_lshl_add_u64 v[8:9], v[8:9], 0, s[46:47]
	s_add_i32 s38, s38, -1
	s_cmp_lg_u32 s38, 0
	s_cbranch_scc1 .Lp3_fast_loop
	s_waitcnt vmcnt(45)
	v_cvt_pk_bf16_f32 v148, v0, v1
	v_cvt_pk_bf16_f32 v149, v2, v3
	global_store_dwordx2 v6, v[148:149], s[36:37]
	v_lshlrev_b32_e32 v150, 16, v100
	v_and_b32_e32 v151, 0xffff0000, v100
	v_lshlrev_b32_e32 v152, 16, v101
	v_and_b32_e32 v153, 0xffff0000, v101
	v_fma_f32 v0, v0, v132, v150
	v_fma_f32 v1, v1, v132, v151
	v_fma_f32 v2, v2, v132, v152
	v_fma_f32 v3, v3, v132, v153
	s_add_u32 s36, s36, 0x20000
	s_addc_u32 s37, s37, 0
	s_waitcnt vmcnt(43)
	v_cvt_pk_bf16_f32 v154, v0, v1
	v_cvt_pk_bf16_f32 v155, v2, v3
	global_store_dwordx2 v6, v[154:155], s[36:37]
	v_lshlrev_b32_e32 v150, 16, v102
	v_and_b32_e32 v151, 0xffff0000, v102
	v_lshlrev_b32_e32 v152, 16, v103
	v_and_b32_e32 v153, 0xffff0000, v103
	v_fma_f32 v0, v0, v133, v150
	v_fma_f32 v1, v1, v133, v151
	v_fma_f32 v2, v2, v133, v152
	v_fma_f32 v3, v3, v133, v153
	s_add_u32 s36, s36, 0x20000
	s_addc_u32 s37, s37, 0
	s_waitcnt vmcnt(41)
	v_cvt_pk_bf16_f32 v148, v0, v1
	v_cvt_pk_bf16_f32 v149, v2, v3
	global_store_dwordx2 v6, v[148:149], s[36:37]
	v_lshlrev_b32_e32 v150, 16, v104
	v_and_b32_e32 v151, 0xffff0000, v104
	v_lshlrev_b32_e32 v152, 16, v105
	v_and_b32_e32 v153, 0xffff0000, v105
	v_fma_f32 v0, v0, v134, v150
	v_fma_f32 v1, v1, v134, v151
	v_fma_f32 v2, v2, v134, v152
	v_fma_f32 v3, v3, v134, v153
	s_add_u32 s36, s36, 0x20000
	s_addc_u32 s37, s37, 0
	s_waitcnt vmcnt(39)
	v_cvt_pk_bf16_f32 v154, v0, v1
	v_cvt_pk_bf16_f32 v155, v2, v3
	global_store_dwordx2 v6, v[154:155], s[36:37]
	v_lshlrev_b32_e32 v150, 16, v106
	v_and_b32_e32 v151, 0xffff0000, v106
	v_lshlrev_b32_e32 v152, 16, v107
	v_and_b32_e32 v153, 0xffff0000, v107
	v_fma_f32 v0, v0, v135, v150
	v_fma_f32 v1, v1, v135, v151
	v_fma_f32 v2, v2, v135, v152
	v_fma_f32 v3, v3, v135, v153
	s_add_u32 s36, s36, 0x20000
	s_addc_u32 s37, s37, 0
	s_waitcnt vmcnt(37)
	v_cvt_pk_bf16_f32 v148, v0, v1
	v_cvt_pk_bf16_f32 v149, v2, v3
	global_store_dwordx2 v6, v[148:149], s[36:37]
	v_lshlrev_b32_e32 v150, 16, v108
	v_and_b32_e32 v151, 0xffff0000, v108
	v_lshlrev_b32_e32 v152, 16, v109
	v_and_b32_e32 v153, 0xffff0000, v109
	v_fma_f32 v0, v0, v136, v150
	v_fma_f32 v1, v1, v136, v151
	v_fma_f32 v2, v2, v136, v152
	v_fma_f32 v3, v3, v136, v153
	s_add_u32 s36, s36, 0x20000
	s_addc_u32 s37, s37, 0
	s_waitcnt vmcnt(35)
	v_cvt_pk_bf16_f32 v154, v0, v1
	v_cvt_pk_bf16_f32 v155, v2, v3
	global_store_dwordx2 v6, v[154:155], s[36:37]
	v_lshlrev_b32_e32 v150, 16, v110
	v_and_b32_e32 v151, 0xffff0000, v110
	v_lshlrev_b32_e32 v152, 16, v111
	v_and_b32_e32 v153, 0xffff0000, v111
	v_fma_f32 v0, v0, v137, v150
	v_fma_f32 v1, v1, v137, v151
	v_fma_f32 v2, v2, v137, v152
	v_fma_f32 v3, v3, v137, v153
	s_add_u32 s36, s36, 0x20000
	s_addc_u32 s37, s37, 0
	s_waitcnt vmcnt(33)
; __device__ __forceinline__ float bf2f(unsigned v) { return __uint_as_float(v << 16); }
; __device__ __forceinline__ unsigned pk2(float lo, float hi) { f32x2 v; v.x = lo; v.y = hi; return __builtin_bit_cast(unsigned, __builtin_convertvector(v, hwbf2)); }
; __global__ void __launch_bounds__(512, 2) fwd_kernel(Args a) {
;     ...
;             for (int c = 0; c < nch; ++c) {
;                 u32x2* p = (u32x2*)(sst + ((size_t)(slot0 + c) * 8 + h) * 8192 + e4);
;                 const u32x2 w = *p; const float d = cdec[(size_t)(slot0 + c) * 8 + h];
;                 u32x2 o; o.x = pk2(hc[0], hc[1]); o.y = pk2(hc[2], hc[3]); *p = o;
;                 hc[0] = hc[0] * d + bf2f(w.x & 0xffff); hc[1] = hc[1] * d + bf2f(w.x >> 16); hc[2] = hc[2] * d + bf2f(w.y & 0xffff); hc[3] = hc[3] * d + bf2f(w.y >> 16);
	v_cvt_pk_bf16_f32 v148, v0, v1
	v_cvt_pk_bf16_f32 v149, v2, v3
	global_store_dwordx2 v6, v[148:149], s[36:37]
	v_lshlrev_b32_e32 v150, 16, v112
	v_and_b32_e32 v151, 0xffff0000, v112
	v_lshlrev_b32_e32 v152, 16, v113
	v_and_b32_e32 v153, 0xffff0000, v113
	v_fma_f32 v0, v0, v138, v150
	v_fma_f32 v1, v1, v138, v151
	v_fma_f32 v2, v2, v138, v152
	v_fma_f32 v3, v3, v138, v153
	s_add_u32 s36, s36, 0x20000
	s_addc_u32 s37, s37, 0
	s_waitcnt vmcnt(31)
	v_cvt_pk_bf16_f32 v154, v0, v1
	v_cvt_pk_bf16_f32 v155, v2, v3
	global_store_dwordx2 v6, v[154:155], s[36:37]
	v_lshlrev_b32_e32 v150, 16, v114
	v_and_b32_e32 v151, 0xffff0000, v114
	v_lshlrev_b32_e32 v152, 16, v115
	v_and_b32_e32 v153, 0xffff0000, v115
	v_fma_f32 v0, v0, v139, v150
	v_fma_f32 v1, v1, v139, v151
	v_fma_f32 v2, v2, v139, v152
	v_fma_f32 v3, v3, v139, v153
	s_add_u32 s36, s36, 0x20000
	s_addc_u32 s37, s37, 0
	s_waitcnt vmcnt(29)
	v_cvt_pk_bf16_f32 v148, v0, v1
	v_cvt_pk_bf16_f32 v149, v2, v3
	global_store_dwordx2 v6, v[148:149], s[36:37]
	v_lshlrev_b32_e32 v150, 16, v116
	v_and_b32_e32 v151, 0xffff0000, v116
	v_lshlrev_b32_e32 v152, 16, v117
	v_and_b32_e32 v153, 0xffff0000, v117
	v_fma_f32 v0, v0, v140, v150
	v_fma_f32 v1, v1, v140, v151
	v_fma_f32 v2, v2, v140, v152
	v_fma_f32 v3, v3, v140, v153
	s_add_u32 s36, s36, 0x20000
	s_addc_u32 s37, s37, 0
	s_waitcnt vmcnt(27)
	v_cvt_pk_bf16_f32 v154, v0, v1
	v_cvt_pk_bf16_f32 v155, v2, v3
	global_store_dwordx2 v6, v[154:155], s[36:37]
	v_lshlrev_b32_e32 v150, 16, v118
	v_and_b32_e32 v151, 0xffff0000, v118
	v_lshlrev_b32_e32 v152, 16, v119
	v_and_b32_e32 v153, 0xffff0000, v119
	v_fma_f32 v0, v0, v141, v150
	v_fma_f32 v1, v1, v141, v151
	v_fma_f32 v2, v2, v141, v152
	v_fma_f32 v3, v3, v141, v153
	s_add_u32 s36, s36, 0x20000
	s_addc_u32 s37, s37, 0
	s_waitcnt vmcnt(25)
	v_cvt_pk_bf16_f32 v148, v0, v1
	v_cvt_pk_bf16_f32 v149, v2, v3
	global_store_dwordx2 v6, v[148:149], s[36:37]
	v_lshlrev_b32_e32 v150, 16, v120
	v_and_b32_e32 v151, 0xffff0000, v120
	v_lshlrev_b32_e32 v152, 16, v121
	v_and_b32_e32 v153, 0xffff0000, v121
	v_fma_f32 v0, v0, v142, v150
	v_fma_f32 v1, v1, v142, v151
	v_fma_f32 v2, v2, v142, v152
	v_fma_f32 v3, v3, v142, v153
	s_add_u32 s36, s36, 0x20000
	s_addc_u32 s37, s37, 0
	s_waitcnt vmcnt(23)
	v_cvt_pk_bf16_f32 v154, v0, v1
	v_cvt_pk_bf16_f32 v155, v2, v3
	global_store_dwordx2 v6, v[154:155], s[36:37]
	v_lshlrev_b32_e32 v150, 16, v122
	v_and_b32_e32 v151, 0xffff0000, v122
	v_lshlrev_b32_e32 v152, 16, v123
	v_and_b32_e32 v153, 0xffff0000, v123
	v_fma_f32 v0, v0, v143, v150
	v_fma_f32 v1, v1, v143, v151
	v_fma_f32 v2, v2, v143, v152
	v_fma_f32 v3, v3, v143, v153
	s_add_u32 s36, s36, 0x20000
	s_addc_u32 s37, s37, 0
	s_waitcnt vmcnt(21)
	v_cvt_pk_bf16_f32 v148, v0, v1
	v_cvt_pk_bf16_f32 v149, v2, v3
	global_store_dwordx2 v6, v[148:149], s[36:37]
	v_lshlrev_b32_e32 v150, 16, v124
	v_and_b32_e32 v151, 0xffff0000, v124
	v_lshlrev_b32_e32 v152, 16, v125
	v_and_b32_e32 v153, 0xffff0000, v125
	v_fma_f32 v0, v0, v144, v150
	v_fma_f32 v1, v1, v144, v151
	v_fma_f32 v2, v2, v144, v152
	v_fma_f32 v3, v3, v144, v153
	s_add_u32 s36, s36, 0x20000
	s_addc_u32 s37, s37, 0
	s_waitcnt vmcnt(19)
	v_cvt_pk_bf16_f32 v154, v0, v1
	v_cvt_pk_bf16_f32 v155, v2, v3
	global_store_dwordx2 v6, v[154:155], s[36:37]
	v_lshlrev_b32_e32 v150, 16, v126
	v_and_b32_e32 v151, 0xffff0000, v126
	v_lshlrev_b32_e32 v152, 16, v127
	v_and_b32_e32 v153, 0xffff0000, v127
	v_fma_f32 v0, v0, v145, v150
	v_fma_f32 v1, v1, v145, v151
	v_fma_f32 v2, v2, v145, v152
	v_fma_f32 v3, v3, v145, v153
	s_add_u32 s36, s36, 0x20000
	s_addc_u32 s37, s37, 0
	s_waitcnt vmcnt(17)
	v_cvt_pk_bf16_f32 v148, v0, v1
	v_cvt_pk_bf16_f32 v149, v2, v3
	global_store_dwordx2 v6, v[148:149], s[36:37]
	v_lshlrev_b32_e32 v150, 16, v128
	v_and_b32_e32 v151, 0xffff0000, v128
	v_lshlrev_b32_e32 v152, 16, v129
	v_and_b32_e32 v153, 0xffff0000, v129
	v_fma_f32 v0, v0, v146, v150
	v_fma_f32 v1, v1, v146, v151
	v_fma_f32 v2, v2, v146, v152
	v_fma_f32 v3, v3, v146, v153
	s_add_u32 s36, s36, 0x20000
	s_addc_u32 s37, s37, 0
	s_waitcnt vmcnt(15)
	v_cvt_pk_bf16_f32 v154, v0, v1
	v_cvt_pk_bf16_f32 v155, v2, v3
	global_store_dwordx2 v6, v[154:155], s[36:37]
	v_lshlrev_b32_e32 v150, 16, v130
	v_and_b32_e32 v151, 0xffff0000, v130
	v_lshlrev_b32_e32 v152, 16, v131
	v_and_b32_e32 v153, 0xffff0000, v131
	v_fma_f32 v0, v0, v147, v150
	v_fma_f32 v1, v1, v147, v151
	v_fma_f32 v2, v2, v147, v152
	v_fma_f32 v3, v3, v147, v153
	s_add_u32 s36, s36, 0x20000
	s_addc_u32 s37, s37, 0
	s_branch .Lp3_join

; __device__ __forceinline__ float bf2f(unsigned v) { return __uint_as_float(v << 16); }
; __device__ __forceinline__ unsigned pk2(float lo, float hi) { f32x2 v; v.x = lo; v.y = hi; return __builtin_bit_cast(unsigned, __builtin_convertvector(v, hwbf2)); }
; __global__ void __launch_bounds__(512, 2) fwd_kernel(Args a) {
;     ...
;         for (int i = bx * 512 + tid; i < 16 * 8 * 2048; i += G * 512) {
;             const int sq = i >> 14, h = (i >> 11) & 7, e4 = (i & 2047) * 4;
;             const bool smp = sq >= 8; const int b = sq & 7;
;             const int nch = smp ? 1 : NCHUNK, slot0 = smp ? NBATCH * NCHUNK + b : b * NCHUNK;
;             f32x4 hc = (f32x4){0.f, 0.f, 0.f, 0.f};
;             if (smp) hc = *(const f32x4*)(a.in[I_SSSD] + ((size_t)(b * 8 + h) * 8192 + e4));
;             for (int c = 0; c < nch; ++c) {
;                 u32x2* p = (u32x2*)(sst + ((size_t)(slot0 + c) * 8 + h) * 8192 + e4);
;                 const u32x2 w = *p; const float d = cdec[(size_t)(slot0 + c) * 8 + h];
;                 u32x2 o; o.x = pk2(hc[0], hc[1]); o.y = pk2(hc[2], hc[3]); *p = o;
;                 hc[0] = hc[0] * d + bf2f(w.x & 0xffff); hc[1] = hc[1] * d + bf2f(w.x >> 16); hc[2] = hc[2] * d + bf2f(w.y & 0xffff); hc[3] = hc[3] * d + bf2f(w.y >> 16);
;             }
;             *(f32x4*)(a.out + (smp ? O_SSDS : O_SSDP) + ((size_t)(b * 8 + h) * 8192 + e4)) = hc;
.Lp3_join:
	s_or_b64 exec, exec, s[0:1]
	v_cndmask_b32_e32 v6, v12, v13, vcc
	v_add_u32_e32 v14, s16, v14
	v_lshl_add_u64 v[8:9], s[86:87], 0, v[6:7]
	v_lshlrev_b32_e32 v6, 2, v15
	v_cmp_lt_i32_e32 vcc, s18, v14
	v_lshl_add_u64 v[8:9], v[8:9], 0, v[6:7]
	s_or_b64 s[10:11], vcc, s[10:11]
	v_add_u32_e32 v5, s17, v5
	global_store_dwordx4 v[8:9], v[0:3], off
	s_andn2_b64 exec, exec, s[10:11]
	s_cbranch_execnz .LBB0_537
